# rope pass also writes selected-branch K in MFMA-fragment order (8 MB in free workspace tail); SEL loop K loads become 1 KB contiguous per instruction
# speedup vs baseline: 1.0775x; 1.0118x over previous
.LBB0_301:
	s_add_i32 s23, s23, -2
	s_mov_b64 s[6:7], 0x2800
	v_lshl_add_u64 v[48:49], v[48:49], 0, s[6:7]
	v_lshl_add_u64 v[50:51], v[50:51], 0, s[78:79]
	v_lshl_add_u64 v[52:53], v[52:53], 0, s[86:87]
	v_add_co_u32_e32 v144, vcc, 0x2080000, v54
	s_nop 1
	v_addc_co_u32_e32 v145, vcc, 0, v55, vcc
	global_load_dwordx4 v[146:149], v[144:145], off offset:128
	global_load_dwordx4 v[150:153], v[144:145], off offset:192
	v_add_co_u32_e32 v144, vcc, 0x2090000, v54
	s_nop 1
	v_addc_co_u32_e32 v145, vcc, 0, v55, vcc
	global_load_dwordx4 v[154:157], v[144:145], off offset:128
	global_load_dwordx4 v[158:161], v[144:145], off offset:192
	v_add_co_u32_e32 v144, vcc, 0x20a0000, v54
	s_nop 1
	v_addc_co_u32_e32 v145, vcc, 0, v55, vcc
	global_load_dwordx4 v[162:165], v[144:145], off offset:128
	global_load_dwordx4 v[166:169], v[144:145], off offset:192
	v_add_co_u32_e32 v144, vcc, 0x20b0000, v54
	s_nop 1
	v_addc_co_u32_e32 v145, vcc, 0, v55, vcc
	global_load_dwordx4 v[170:173], v[144:145], off offset:128
	global_load_dwordx4 v[174:177], v[144:145], off offset:192
	v_add_co_u32_e32 v144, vcc, 0x20c0000, v54
	s_nop 1
	v_addc_co_u32_e32 v145, vcc, 0, v55, vcc
	global_load_dwordx4 v[178:181], v[144:145], off offset:128
	global_load_dwordx4 v[182:185], v[144:145], off offset:192
	v_add_co_u32_e32 v144, vcc, 0x20d0000, v54
	s_nop 1
	v_addc_co_u32_e32 v145, vcc, 0, v55, vcc
	global_load_dwordx4 v[186:189], v[144:145], off offset:128
	global_load_dwordx4 v[190:193], v[144:145], off offset:192
	v_add_co_u32_e32 v144, vcc, 0x20e0000, v54
	s_nop 1
	v_addc_co_u32_e32 v145, vcc, 0, v55, vcc
	global_load_dwordx4 v[194:197], v[144:145], off offset:128
	global_load_dwordx4 v[200:203], v[144:145], off offset:192
	v_add_co_u32_e32 v144, vcc, 0x20f0000, v54
	s_nop 1
	v_addc_co_u32_e32 v145, vcc, 0, v55, vcc
	global_load_dwordx4 v[204:207], v[144:145], off offset:128
	global_load_dwordx4 v[208:211], v[144:145], off offset:192
	s_cmp_eq_u32 s23, 0
	s_waitcnt vmcnt(14) lgkmcnt(0)
	v_mfma_f32_16x16x32_bf16 v[30:33], v[146:149], v[34:37], v[30:33]
	v_mfma_f32_16x16x32_bf16 v[30:33], v[150:153], v[38:41], v[30:33]
	s_waitcnt vmcnt(12)
	v_mfma_f32_16x16x32_bf16 v[26:29], v[154:157], v[34:37], v[26:29]
	v_mfma_f32_16x16x32_bf16 v[26:29], v[158:161], v[38:41], v[26:29]
	s_waitcnt vmcnt(10)
	v_mfma_f32_16x16x32_bf16 v[22:25], v[162:165], v[34:37], v[22:25]
	v_mfma_f32_16x16x32_bf16 v[22:25], v[166:169], v[38:41], v[22:25]
	s_waitcnt vmcnt(8)
	v_mfma_f32_16x16x32_bf16 v[18:21], v[170:173], v[34:37], v[18:21]
	v_mfma_f32_16x16x32_bf16 v[18:21], v[174:177], v[38:41], v[18:21]
	s_waitcnt vmcnt(6)
	v_mfma_f32_16x16x32_bf16 v[14:17], v[178:181], v[34:37], v[14:17]
	v_mfma_f32_16x16x32_bf16 v[14:17], v[182:185], v[38:41], v[14:17]
	s_waitcnt vmcnt(4)
	v_mfma_f32_16x16x32_bf16 v[10:13], v[186:189], v[34:37], v[10:13]
	v_mfma_f32_16x16x32_bf16 v[10:13], v[190:193], v[38:41], v[10:13]
	s_waitcnt vmcnt(2)
	v_mfma_f32_16x16x32_bf16 v[6:9], v[194:197], v[34:37], v[6:9]
	v_mfma_f32_16x16x32_bf16 v[6:9], v[200:203], v[38:41], v[6:9]
	s_waitcnt vmcnt(0)
	v_mfma_f32_16x16x32_bf16 v[2:5], v[204:207], v[34:37], v[2:5]
	v_mfma_f32_16x16x32_bf16 v[2:5], v[208:211], v[38:41], v[2:5]
	s_cbranch_scc1 .LBB0_310

.LBB0_306:
	v_lshl_add_u64 v[54:55], v[46:47], 0, v[52:53]
	s_mov_b64 s[16:17], -1
	v_add_co_u32_e32 v144, vcc, 0x2080000, v54
	s_nop 1
	v_addc_co_u32_e32 v145, vcc, 0, v55, vcc
	global_load_dwordx4 v[146:149], v[144:145], off
	global_load_dwordx4 v[150:153], v[144:145], off offset:64
	v_add_co_u32_e32 v144, vcc, 0x2090000, v54
	s_nop 1
	v_addc_co_u32_e32 v145, vcc, 0, v55, vcc
	global_load_dwordx4 v[154:157], v[144:145], off
	global_load_dwordx4 v[158:161], v[144:145], off offset:64
	v_add_co_u32_e32 v144, vcc, 0x20a0000, v54
	s_nop 1
	v_addc_co_u32_e32 v145, vcc, 0, v55, vcc
	global_load_dwordx4 v[162:165], v[144:145], off
	global_load_dwordx4 v[166:169], v[144:145], off offset:64
	v_add_co_u32_e32 v144, vcc, 0x20b0000, v54
	s_nop 1
	v_addc_co_u32_e32 v145, vcc, 0, v55, vcc
	global_load_dwordx4 v[170:173], v[144:145], off
	global_load_dwordx4 v[174:177], v[144:145], off offset:64
	v_add_co_u32_e32 v144, vcc, 0x20c0000, v54
	s_nop 1
	v_addc_co_u32_e32 v145, vcc, 0, v55, vcc
	global_load_dwordx4 v[178:181], v[144:145], off
	global_load_dwordx4 v[182:185], v[144:145], off offset:64
	v_add_co_u32_e32 v144, vcc, 0x20d0000, v54
	s_nop 1
	v_addc_co_u32_e32 v145, vcc, 0, v55, vcc
	global_load_dwordx4 v[186:189], v[144:145], off
	global_load_dwordx4 v[190:193], v[144:145], off offset:64
	v_add_co_u32_e32 v144, vcc, 0x20e0000, v54
	s_nop 1
	v_addc_co_u32_e32 v145, vcc, 0, v55, vcc
	global_load_dwordx4 v[194:197], v[144:145], off
	global_load_dwordx4 v[200:203], v[144:145], off offset:64
	v_add_co_u32_e32 v144, vcc, 0x20f0000, v54
	s_nop 1
	v_addc_co_u32_e32 v145, vcc, 0, v55, vcc
	global_load_dwordx4 v[204:207], v[144:145], off
	global_load_dwordx4 v[208:211], v[144:145], off offset:64
	s_waitcnt vmcnt(14) lgkmcnt(0)
	v_mfma_f32_16x16x32_bf16 v[30:33], v[146:149], v[34:37], v[30:33]
	v_mfma_f32_16x16x32_bf16 v[30:33], v[150:153], v[38:41], v[30:33]
	s_waitcnt vmcnt(12)
	v_mfma_f32_16x16x32_bf16 v[26:29], v[154:157], v[34:37], v[26:29]
	v_mfma_f32_16x16x32_bf16 v[26:29], v[158:161], v[38:41], v[26:29]
	s_waitcnt vmcnt(10)
	v_mfma_f32_16x16x32_bf16 v[22:25], v[162:165], v[34:37], v[22:25]
	v_mfma_f32_16x16x32_bf16 v[22:25], v[166:169], v[38:41], v[22:25]
	s_waitcnt vmcnt(8)
	v_mfma_f32_16x16x32_bf16 v[18:21], v[170:173], v[34:37], v[18:21]
	v_mfma_f32_16x16x32_bf16 v[18:21], v[174:177], v[38:41], v[18:21]
	s_waitcnt vmcnt(6)
	v_mfma_f32_16x16x32_bf16 v[14:17], v[178:181], v[34:37], v[14:17]
	v_mfma_f32_16x16x32_bf16 v[14:17], v[182:185], v[38:41], v[14:17]
	s_waitcnt vmcnt(4)
	v_mfma_f32_16x16x32_bf16 v[10:13], v[186:189], v[34:37], v[10:13]
	v_mfma_f32_16x16x32_bf16 v[10:13], v[190:193], v[38:41], v[10:13]
	s_waitcnt vmcnt(2)
	v_mfma_f32_16x16x32_bf16 v[6:9], v[194:197], v[34:37], v[6:9]
	v_mfma_f32_16x16x32_bf16 v[6:9], v[200:203], v[38:41], v[6:9]
	s_waitcnt vmcnt(0)
	v_mfma_f32_16x16x32_bf16 v[2:5], v[204:207], v[34:37], v[2:5]
	v_mfma_f32_16x16x32_bf16 v[2:5], v[208:211], v[38:41], v[2:5]
	v_add_co_u32_e32 v38, vcc, 0x8b8a000, v58
	s_nop 1
	v_addc_co_u32_e32 v39, vcc, 0, v59, vcc
	global_load_dwordx4 v[34:37], v[38:39], off offset:2048
	s_nop 0
	global_load_dwordx4 v[38:41], v[38:39], off offset:2112
	s_and_b64 vcc, exec, s[6:7]
	s_cbranch_vccnz .LBB0_308
	s_mov_b64 s[16:17], 0

.LBB0_330:
	v_readlane_b32 s4, v254, 2
	s_nop 1
	v_add_u32_e32 v26, s4, v8
	s_mov_b32 s4, 0x20000
	v_cmp_gt_i32_e32 vcc, s4, v26
	s_and_saveexec_b64 s[4:5], vcc
	s_cbranch_execz .LBB0_357
	s_mov_b64 s[6:7], 0x2389000
	v_lshl_add_u64 v[20:21], v[46:47], 0, s[6:7]
	s_mov_b64 s[100:101], 0x7f89000
	v_lshl_add_u64 v[56:57], v[46:47], 0, s[100:101]
	s_mov_b32 s99, 0
	s_mov_b64 s[6:7], 0
	s_branch .LBB0_333

.LBB0_333:
	v_lshrrev_b32_e32 v58, 7, v26
	v_lshlrev_b32_e32 v58, 12, v58
	v_and_b32_e32 v59, 2, v26
	v_lshlrev_b32_e32 v59, 9, v59
	v_or_b32_e32 v58, v58, v59
	v_and_b32_e32 v59, 1, v26
	v_lshlrev_b32_e32 v59, 4, v59
	v_or_b32_e32 v58, v58, v59
	v_bfe_u32 v59, v26, 2, 5
	v_lshlrev_b32_e32 v59, 5, v59
	v_or_b32_e32 v58, v58, v59
	v_add_co_u32_e32 v60, vcc, v56, v58
	s_nop 1
	v_addc_co_u32_e32 v61, vcc, 0, v57, vcc
	v_ashrrev_i32_e32 v22, 2, v26
	v_ashrrev_i32_e32 v23, 31, v22
	v_lshlrev_b32_e32 v0, 3, v26
	v_and_b32_e32 v24, 24, v0
	v_lshlrev_b64 v[2:3], 8, v[22:23]
	v_lshl_add_u64 v[2:3], v[20:21], 0, v[2:3]
	v_lshlrev_b32_e32 v0, 3, v24
	v_lshl_add_u64 v[14:15], v[2:3], 0, v[0:1]
	global_load_dwordx4 v[2:5], v[14:15], off
	global_load_dwordx4 v[6:9], v[14:15], off offset:16
	global_load_dwordx4 v[10:13], v[14:15], off offset:32
	s_nop 0
	global_load_dwordx4 v[14:17], v[14:15], off offset:48
	v_mad_i64_i32 v[22:23], s[8:9], v22, s61, v[18:19]
	v_lshlrev_b32_e32 v0, 1, v24
	v_lshl_add_u64 v[22:23], v[22:23], 0, v[0:1]
	s_mov_b32 s10, 0
	s_movk_i32 s11, 0x200
	s_movk_i32 s12, 0x100
	s_waitcnt vmcnt(0) lgkmcnt(0)
	v_mov_b32_e32 v24, v15
	v_mov_b32_e32 v25, v17
	v_mov_b32_e32 v15, v16
	v_mov_b32_e32 v16, v11
	v_mov_b32_e32 v17, v13
	v_mov_b32_e32 v11, v12
	v_mov_b32_e32 v12, v7
	v_mov_b32_e32 v13, v9
	v_mov_b32_e32 v7, v8
	v_mov_b32_e32 v8, v3
	v_mov_b32_e32 v9, v5
	v_mov_b32_e32 v3, v4
	s_branch .LBB0_335
.LBB0_334:
	v_lshl_add_u64 v[4:5], s[74:75], 1, v[22:23]
	s_and_b32 s98, s74, 64
	s_lshl_b32 s98, s98, 16
	v_lshl_add_u64 v[62:63], v[60:61], 0, s[98:99]
	s_andn2_b32 s98, s74, 64
	s_cmp_eq_u32 s98, 0x300
	s_cselect_b64 s[100:101], -1, 0
	global_load_dwordx4 v[28:31], v[4:5], off
	global_load_dwordx4 v[32:35], v[4:5], off offset:64
	s_add_i32 s10, s10, 3
	s_addk_i32 s11, 0xc0
	s_addk_i32 s12, 0x180
	s_cmpk_eq_i32 s11, 0x740
	s_waitcnt vmcnt(0) lgkmcnt(0)
	v_lshlrev_b32_e32 v36, 16, v28
	v_lshlrev_b32_e32 v38, 16, v32
	v_and_b32_e32 v39, 0xffff0000, v32
	v_and_b32_e32 v37, 0xffff0000, v28
	v_pk_mul_f32 v[40:41], v[2:3], v[38:39]
	v_pk_mul_f32 v[38:39], v[8:9], v[38:39]
	v_lshlrev_b32_e32 v32, 16, v33
	v_and_b32_e32 v33, 0xffff0000, v33
	v_pk_fma_f32 v[40:41], v[8:9], v[36:37], v[40:41]
	v_pk_fma_f32 v[36:37], v[2:3], v[36:37], v[38:39] neg_lo:[0,0,1] neg_hi:[0,0,1]
	v_lshlrev_b32_e32 v28, 16, v29
	v_and_b32_e32 v29, 0xffff0000, v29
	v_pk_mul_f32 v[38:39], v[6:7], v[32:33]
	v_pk_mul_f32 v[32:33], v[12:13], v[32:33]
	v_lshlrev_b32_e32 v42, 16, v34
	v_and_b32_e32 v43, 0xffff0000, v34
	v_pk_fma_f32 v[38:39], v[12:13], v[28:29], v[38:39]
	v_pk_fma_f32 v[32:33], v[6:7], v[28:29], v[32:33] neg_lo:[0,0,1] neg_hi:[0,0,1]
	v_lshlrev_b32_e32 v28, 16, v30
	v_and_b32_e32 v29, 0xffff0000, v30
	v_pk_mul_f32 v[44:45], v[10:11], v[42:43]
	v_pk_mul_f32 v[42:43], v[16:17], v[42:43]
	v_pk_fma_f32 v[44:45], v[16:17], v[28:29], v[44:45]
	v_pk_fma_f32 v[42:43], v[10:11], v[28:29], v[42:43] neg_lo:[0,0,1] neg_hi:[0,0,1]
	v_lshlrev_b32_e32 v28, 16, v31
	v_and_b32_e32 v29, 0xffff0000, v31
	v_lshlrev_b32_e32 v30, 16, v35
	v_and_b32_e32 v31, 0xffff0000, v35
	v_pk_mul_f32 v[34:35], v[14:15], v[30:31]
	v_pk_mul_f32 v[30:31], v[24:25], v[30:31]
	v_pk_fma_f32 v[34:35], v[24:25], v[28:29], v[34:35]
	v_pk_fma_f32 v[46:47], v[14:15], v[28:29], v[30:31] neg_lo:[0,0,1] neg_hi:[0,0,1]
	v_cvt_pk_bf16_f32 v28, v36, v37
	v_cvt_pk_bf16_f32 v29, v32, v33
	v_cvt_pk_bf16_f32 v30, v42, v43
	v_cvt_pk_bf16_f32 v31, v46, v47
	global_store_dwordx4 v[4:5], v[28:31], off
	s_mov_b64 vcc, s[100:101]
	s_cbranch_vccz .Lkf_c1
	global_store_dwordx4 v[62:63], v[28:31], off
.Lkf_c1:
	s_nop 1
	v_cvt_pk_bf16_f32 v28, v40, v41
	v_cvt_pk_bf16_f32 v29, v38, v39
	v_cvt_pk_bf16_f32 v30, v44, v45
	v_cvt_pk_bf16_f32 v31, v34, v35
	global_store_dwordx4 v[4:5], v[28:31], off offset:64
	s_mov_b64 vcc, s[100:101]
	s_cbranch_vccz .Lkf_c2
	global_store_dwordx4 v[62:63], v[28:31], off offset:2048
.Lkf_c2:
	s_cbranch_scc1 .LBB0_332

.LBB0_341:
	v_lshl_add_u64 v[4:5], s[74:75], 1, v[22:23]
	s_and_b32 s98, s74, 64
	s_lshl_b32 s98, s98, 16
	v_lshl_add_u64 v[62:63], v[60:61], 0, s[98:99]
	s_andn2_b32 s98, s74, 64
	s_cmp_eq_u32 s98, 0x300
	s_cselect_b64 s[100:101], -1, 0
	global_load_dwordx4 v[28:31], v[4:5], off
	global_load_dwordx4 v[32:35], v[4:5], off offset:64
	s_mov_b64 s[8:9], -1
	s_cmp_lt_u32 s10, 7
	s_waitcnt vmcnt(0) lgkmcnt(0)
	v_lshlrev_b32_e32 v36, 16, v28
	v_lshlrev_b32_e32 v38, 16, v32
	v_and_b32_e32 v39, 0xffff0000, v32
	v_and_b32_e32 v37, 0xffff0000, v28
	v_pk_mul_f32 v[40:41], v[2:3], v[38:39]
	v_pk_mul_f32 v[38:39], v[8:9], v[38:39]
	v_lshlrev_b32_e32 v32, 16, v33
	v_and_b32_e32 v33, 0xffff0000, v33
	v_pk_fma_f32 v[40:41], v[8:9], v[36:37], v[40:41]
	v_pk_fma_f32 v[36:37], v[2:3], v[36:37], v[38:39] neg_lo:[0,0,1] neg_hi:[0,0,1]
	v_lshlrev_b32_e32 v28, 16, v29
	v_and_b32_e32 v29, 0xffff0000, v29
	v_pk_mul_f32 v[38:39], v[6:7], v[32:33]
	v_pk_mul_f32 v[32:33], v[12:13], v[32:33]
	v_lshlrev_b32_e32 v42, 16, v34
	v_and_b32_e32 v43, 0xffff0000, v34
	v_pk_fma_f32 v[38:39], v[12:13], v[28:29], v[38:39]
	v_pk_fma_f32 v[32:33], v[6:7], v[28:29], v[32:33] neg_lo:[0,0,1] neg_hi:[0,0,1]
	v_lshlrev_b32_e32 v28, 16, v30
	v_and_b32_e32 v29, 0xffff0000, v30
	v_pk_mul_f32 v[44:45], v[10:11], v[42:43]
	v_pk_mul_f32 v[42:43], v[16:17], v[42:43]
	v_pk_fma_f32 v[44:45], v[16:17], v[28:29], v[44:45]
	v_pk_fma_f32 v[42:43], v[10:11], v[28:29], v[42:43] neg_lo:[0,0,1] neg_hi:[0,0,1]
	v_lshlrev_b32_e32 v28, 16, v31
	v_and_b32_e32 v29, 0xffff0000, v31
	v_lshlrev_b32_e32 v30, 16, v35
	v_and_b32_e32 v31, 0xffff0000, v35
	v_pk_mul_f32 v[34:35], v[14:15], v[30:31]
	v_pk_mul_f32 v[30:31], v[24:25], v[30:31]
	v_pk_fma_f32 v[34:35], v[24:25], v[28:29], v[34:35]
	v_pk_fma_f32 v[46:47], v[14:15], v[28:29], v[30:31] neg_lo:[0,0,1] neg_hi:[0,0,1]
	v_cvt_pk_bf16_f32 v28, v36, v37
	v_cvt_pk_bf16_f32 v29, v32, v33
	v_cvt_pk_bf16_f32 v30, v42, v43
	v_cvt_pk_bf16_f32 v31, v46, v47
	global_store_dwordx4 v[4:5], v[28:31], off
	s_mov_b64 vcc, s[100:101]
	s_cbranch_vccz .Lkf_a1
	global_store_dwordx4 v[62:63], v[28:31], off

.Lkf_a2:
	s_cbranch_scc1 .LBB0_347
	s_cmp_lt_u32 s10, 11
	s_cbranch_scc1 .LBB0_344
	s_lshl_b32 s8, s10, 6
	s_add_i32 s74, s8, 0x240
	s_mov_b64 s[8:9], 0

.LBB0_349:
	v_lshl_add_u64 v[4:5], s[74:75], 1, v[22:23]
	s_and_b32 s98, s74, 64
	s_lshl_b32 s98, s98, 16
	v_lshl_add_u64 v[62:63], v[60:61], 0, s[98:99]
	s_andn2_b32 s98, s74, 64
	s_cmp_eq_u32 s98, 0x300
	s_cselect_b64 s[100:101], -1, 0
	global_load_dwordx4 v[28:31], v[4:5], off
	global_load_dwordx4 v[32:35], v[4:5], off offset:64
	s_mov_b64 s[8:9], -1
	s_cmp_lt_u32 s10, 6
	s_waitcnt vmcnt(0) lgkmcnt(0)
	v_lshlrev_b32_e32 v36, 16, v28
	v_lshlrev_b32_e32 v38, 16, v32
	v_and_b32_e32 v39, 0xffff0000, v32
	v_and_b32_e32 v37, 0xffff0000, v28
	v_pk_mul_f32 v[40:41], v[2:3], v[38:39]
	v_pk_mul_f32 v[38:39], v[8:9], v[38:39]
	v_lshlrev_b32_e32 v32, 16, v33
	v_and_b32_e32 v33, 0xffff0000, v33
	v_pk_fma_f32 v[40:41], v[8:9], v[36:37], v[40:41]
	v_pk_fma_f32 v[36:37], v[2:3], v[36:37], v[38:39] neg_lo:[0,0,1] neg_hi:[0,0,1]
	v_lshlrev_b32_e32 v28, 16, v29
	v_and_b32_e32 v29, 0xffff0000, v29
	v_pk_mul_f32 v[38:39], v[6:7], v[32:33]
	v_pk_mul_f32 v[32:33], v[12:13], v[32:33]
	v_lshlrev_b32_e32 v42, 16, v34
	v_and_b32_e32 v43, 0xffff0000, v34
	v_pk_fma_f32 v[38:39], v[12:13], v[28:29], v[38:39]
	v_pk_fma_f32 v[32:33], v[6:7], v[28:29], v[32:33] neg_lo:[0,0,1] neg_hi:[0,0,1]
	v_lshlrev_b32_e32 v28, 16, v30
	v_and_b32_e32 v29, 0xffff0000, v30
	v_pk_mul_f32 v[44:45], v[10:11], v[42:43]
	v_pk_mul_f32 v[42:43], v[16:17], v[42:43]
	v_pk_fma_f32 v[44:45], v[16:17], v[28:29], v[44:45]
	v_pk_fma_f32 v[42:43], v[10:11], v[28:29], v[42:43] neg_lo:[0,0,1] neg_hi:[0,0,1]
	v_lshlrev_b32_e32 v28, 16, v31
	v_and_b32_e32 v29, 0xffff0000, v31
	v_lshlrev_b32_e32 v30, 16, v35
	v_and_b32_e32 v31, 0xffff0000, v35
	v_pk_mul_f32 v[34:35], v[14:15], v[30:31]
	v_pk_mul_f32 v[30:31], v[24:25], v[30:31]
	v_pk_fma_f32 v[34:35], v[24:25], v[28:29], v[34:35]
	v_pk_fma_f32 v[46:47], v[14:15], v[28:29], v[30:31] neg_lo:[0,0,1] neg_hi:[0,0,1]
	v_cvt_pk_bf16_f32 v28, v36, v37
	v_cvt_pk_bf16_f32 v29, v32, v33
	v_cvt_pk_bf16_f32 v30, v42, v43
	v_cvt_pk_bf16_f32 v31, v46, v47
	global_store_dwordx4 v[4:5], v[28:31], off
	s_mov_b64 vcc, s[100:101]
	s_cbranch_vccz .Lkf_b1
	global_store_dwordx4 v[62:63], v[28:31], off

.Lkf_b2:
	s_cbranch_scc1 .LBB0_355
	s_cmp_lt_u32 s10, 10
	s_cbranch_scc1 .LBB0_352
	s_lshl_b32 s8, s10, 6
	s_add_i32 s74, s8, 0x280
	s_mov_b64 s[8:9], 0

.LBB0_625:
	v_mov_b32_e32 v0, 0x1400000
	s_add_i32 s82, s18, s16
	v_mad_i64_i32 v[2:3], s[4:5], s16, v0, v[154:155]
	s_ashr_i32 s83, s82, 31
	s_lshl_b32 s74, s24, 7
	s_lshl_b64 s[4:5], s[82:83], 19
	s_waitcnt lgkmcnt(0)
	v_lshl_add_u64 v[148:149], v[2:3], 0, s[74:75]
	v_lshl_add_u64 v[2:3], v[164:165], 0, s[4:5]
	s_lshl_b64 s[4:5], 2, s17
	ds_read_b64 v[152:153], v37 offset:18432
	s_waitcnt lgkmcnt(0)
	s_add_u32 s4, s4, -1
	v_and_b32_e32 v8, 31, v195
	v_ashrrev_i32_e32 v9, 5, v195
	s_addc_u32 s5, s5, -1
	v_mul_u32_u24_e32 v0, 0xa00, v8
	v_lshlrev_b32_e32 v6, 3, v9
	s_and_b64 s[94:95], s[20:21], s[4:5]
	v_lshlrev_b32_e32 v0, 1, v0
	v_ashrrev_i32_e32 v7, 31, v6
	v_lshl_add_u64 v[4:5], v[148:149], 0, v[0:1]
	v_lshlrev_b64 v[6:7], 1, v[6:7]
	s_ff1_i32_b64 s4, s[94:95]
	v_lshl_add_u64 v[180:181], v[4:5], 0, v[6:7]
	v_lshl_add_u64 v[2:3], v[2:3], 0, v[6:7]
	v_lshlrev_b32_e32 v0, 5, v8
	v_mov_b32_e32 v14, v1
	v_mov_b32_e32 v15, v1
	v_lshl_add_u64 v[182:183], v[2:3], 0, v[0:1]
	s_mov_b64 s[100:101], 0x1400000
	s_mov_b32 s99, 0
	v_lshl_add_u64 v[240:241], v[182:183], 0, s[100:101]
	s_lshl_b32 s74, s4, 13
	v_lshl_add_u64 v[4:5], v[240:241], 0, s[74:75]
	global_load_dwordx4 v[118:121], v[4:5], off
	global_load_dwordx4 v[122:125], v[4:5], off offset:1024
	global_load_dwordx4 v[126:129], v[4:5], off offset:2048
	global_load_dwordx4 v[114:117], v[4:5], off offset:3072
	v_lshlrev_b32_e32 v173, 2, v9
	v_mov_b32_e32 v0, v1
	v_mov_b32_e32 v2, v1
	v_mov_b32_e32 v3, v1
	v_mov_b32_e32 v4, v1
	v_mov_b32_e32 v5, v1
	v_mov_b32_e32 v6, v1
	v_mov_b32_e32 v7, v1
	v_mov_b32_e32 v8, v1
	v_mov_b32_e32 v9, v1
	v_mov_b32_e32 v10, v1
	v_mov_b32_e32 v11, v1
	v_mov_b32_e32 v12, v1
	v_mov_b32_e32 v13, v1
	v_mov_b64_e32 v[64:65], v[14:15]
	v_mov_b64_e32 v[48:49], v[14:15]
	v_mov_b64_e32 v[32:33], v[14:15]
	v_mov_b32_e32 v151, 0
	v_mov_b64_e32 v[62:63], v[12:13]
	v_mov_b64_e32 v[60:61], v[10:11]
	v_mov_b64_e32 v[58:59], v[8:9]
	v_mov_b64_e32 v[56:57], v[6:7]
	v_mov_b64_e32 v[54:55], v[4:5]
	v_mov_b64_e32 v[52:53], v[2:3]
	v_mov_b64_e32 v[50:51], v[0:1]
	v_mov_b64_e32 v[46:47], v[12:13]
	v_mov_b64_e32 v[44:45], v[10:11]
	v_mov_b64_e32 v[42:43], v[8:9]
	v_mov_b64_e32 v[40:41], v[6:7]
	v_mov_b64_e32 v[38:39], v[4:5]
	v_mov_b64_e32 v[36:37], v[2:3]
	v_mov_b64_e32 v[34:35], v[0:1]
	v_mov_b64_e32 v[30:31], v[12:13]
	v_mov_b64_e32 v[28:29], v[10:11]
	v_mov_b64_e32 v[26:27], v[8:9]
	v_mov_b64_e32 v[24:25], v[6:7]
	v_mov_b64_e32 v[22:23], v[4:5]
	v_mov_b64_e32 v[20:21], v[2:3]
	v_mov_b64_e32 v[18:19], v[0:1]
	v_mov_b64_e32 v[16:17], v[14:15]
	v_add_u32_e32 v175, 6, v172
	v_add_u32_e32 v184, 5, v172
	s_mov_b32 s8, 0
	v_mov_b32_e32 v203, 0xf149f2ca
	v_mov_b32_e32 v150, v151
	v_mov_b32_e32 v185, 0xf149f2ca
	v_mov_b64_e32 v[14:15], v[12:13]
	v_mov_b64_e32 v[12:13], v[10:11]
	v_mov_b64_e32 v[10:11], v[8:9]
	v_mov_b64_e32 v[8:9], v[6:7]
	v_mov_b64_e32 v[6:7], v[4:5]
	v_mov_b64_e32 v[4:5], v[2:3]
	v_mov_b64_e32 v[2:3], v[0:1]
	s_mov_b32 s83, s4

.LBB0_635:
	v_cndmask_b32_e64 v222, -v248, v0, s[6:7]
	v_fma_f32 v66, v66, s66, -v222
	v_exp_f32_e32 v203, v66
	v_fma_f32 v66, v67, s66, -v222
	v_exp_f32_e32 v204, v66
	v_fma_f32 v66, v68, s66, -v222
	v_exp_f32_e32 v205, v66
	v_fma_f32 v66, v69, s66, -v222
	v_exp_f32_e32 v206, v66
	v_fma_f32 v66, v70, s66, -v222
	v_exp_f32_e32 v207, v66
	v_fma_f32 v66, v71, s66, -v222
	v_exp_f32_e32 v208, v66
	v_fma_f32 v66, v72, s66, -v222
	v_exp_f32_e32 v209, v66
	v_fma_f32 v66, v73, s66, -v222
	v_exp_f32_e32 v210, v66
	v_fma_f32 v66, v74, s66, -v222
	v_exp_f32_e32 v211, v66
	v_fma_f32 v66, v75, s66, -v222
	v_exp_f32_e32 v212, v66
	v_fma_f32 v66, v76, s66, -v222
	v_exp_f32_e32 v213, v66
	v_fma_f32 v66, v77, s66, -v222
	v_exp_f32_e32 v214, v66
	v_fma_f32 v66, v78, s66, -v222
	v_exp_f32_e32 v215, v66
	v_fma_f32 v66, v79, s66, -v222
	v_exp_f32_e32 v216, v66
	v_fma_f32 v66, v80, s66, -v222
	v_exp_f32_e32 v217, v66
	v_fma_f32 v66, v81, s66, -v222
	v_exp_f32_e32 v218, v66
	v_cvt_pk_bf16_f32 v66, v203, v204
	v_cvt_pk_bf16_f32 v67, v205, v206
	v_cvt_pk_bf16_f32 v68, v207, v208
	v_cvt_pk_bf16_f32 v69, v209, v210
	v_cvt_pk_bf16_f32 v70, v211, v212
	v_cvt_pk_bf16_f32 v71, v213, v214
	s_waitcnt vmcnt(0) lgkmcnt(0)
	v_mfma_f32_32x32x16_bf16 v[50:65], v[142:145], v[66:69], v[50:65]
	v_cvt_pk_bf16_f32 v72, v215, v216
	v_cvt_pk_bf16_f32 v73, v217, v218
	s_lshl_b32 s8, s90, 5
	s_add_i32 s8, s8, s91
	s_lshl_b32 s98, s8, 7
	v_lshl_add_u64 v[220:221], v[240:241], 0, s[98:99]
	s_xor_b64 s[6:7], s[56:57], -1
	v_mfma_f32_32x32x16_bf16 v[34:49], v[134:137], v[66:69], v[34:49]
	s_andn2_b64 vcc, exec, s[6:7]
	v_mfma_f32_32x32x16_bf16 v[50:65], v[138:141], v[70:73], v[50:65]
	v_mfma_f32_32x32x16_bf16 v[34:49], v[130:133], v[70:73], v[34:49]
	v_mfma_f32_32x32x16_bf16 v[66:81], v[118:121], v[98:101], 0
	v_mfma_f32_32x32x16_bf16 v[66:81], v[122:125], v[102:105], v[66:81]
	v_mfma_f32_32x32x16_bf16 v[66:81], v[126:129], v[106:109], v[66:81]
	v_mfma_f32_32x32x16_bf16 v[66:81], v[114:117], v[110:113], v[66:81]
	global_load_dwordx4 v[118:121], v[220:221], off
	global_load_dwordx4 v[122:125], v[220:221], off offset:1024
	global_load_dwordx4 v[126:129], v[220:221], off offset:2048
	global_load_dwordx4 v[114:117], v[220:221], off offset:3072
	s_cbranch_vccnz .LBB0_637
	v_cmp_le_i32_e32 vcc, v186, v174
	s_and_b64 vcc, s[4:5], vcc
	s_nop 4
	v_cndmask_b32_e32 v66, v248, v66, vcc
	v_cmp_lt_i32_e32 vcc, v186, v174
	s_and_b64 vcc, s[4:5], vcc
	s_nop 0
	v_cndmask_b32_e32 v67, v248, v67, vcc
	v_cmp_le_i32_e32 vcc, v186, v175
	s_and_b64 vcc, s[4:5], vcc
	s_nop 0
	v_cndmask_b32_e32 v68, v248, v68, vcc
	v_cmp_le_i32_e32 vcc, v186, v184
	s_and_b64 vcc, s[4:5], vcc
	s_nop 0
	v_cndmask_b32_e32 v69, v248, v69, vcc
	v_cmp_le_i32_e32 vcc, v186, v172
	s_and_b64 vcc, s[4:5], vcc
	s_nop 0
	v_cndmask_b32_e32 v70, v248, v70, vcc
	v_cmp_lt_i32_e32 vcc, v186, v172
	s_and_b64 vcc, s[4:5], vcc
	s_nop 0
	v_cndmask_b32_e32 v71, v248, v71, vcc
	v_cmp_le_i32_e32 vcc, v202, v172
	s_and_b64 vcc, s[4:5], vcc
	s_nop 0
	v_cndmask_b32_e32 v72, v248, v72, vcc
	v_cmp_le_i32_e32 vcc, v200, v172
	s_and_b64 vcc, s[4:5], vcc
	s_nop 0
	v_cndmask_b32_e32 v73, v248, v73, vcc
	v_cmp_le_i32_e32 vcc, v192, v172
	s_and_b64 vcc, s[4:5], vcc
	s_nop 0
	v_cndmask_b32_e32 v74, v248, v74, vcc
	v_cmp_le_i32_e32 vcc, v201, v172
	s_and_b64 vcc, s[4:5], vcc
	s_nop 0
	v_cndmask_b32_e32 v75, v248, v75, vcc
	v_cmp_le_i32_e32 vcc, v193, v172
	s_and_b64 vcc, s[4:5], vcc
	s_nop 0
	v_cndmask_b32_e32 v76, v248, v76, vcc
	v_cmp_le_i32_e32 vcc, v191, v172
	s_and_b64 vcc, s[4:5], vcc
	s_nop 0
	v_cndmask_b32_e32 v77, v248, v77, vcc
	v_cmp_le_i32_e32 vcc, v190, v172
	s_and_b64 vcc, s[4:5], vcc
	s_nop 0
	v_cndmask_b32_e32 v78, v248, v78, vcc
	v_cmp_le_i32_e32 vcc, v189, v172
	s_and_b64 vcc, s[4:5], vcc
	s_nop 0
	v_cndmask_b32_e32 v79, v248, v79, vcc
	v_cmp_le_i32_e32 vcc, v188, v172
	s_and_b64 vcc, s[4:5], vcc
	s_nop 0
	v_cndmask_b32_e32 v80, v248, v80, vcc
	v_cmp_le_i32_e32 vcc, v187, v172
	s_and_b64 vcc, s[4:5], vcc
	s_nop 0
	v_cndmask_b32_e32 v81, v248, v81, vcc
